# attention key loop regenerated: ALiBi bias prefilled into QK accumulators, 6-buffer LDS fragment ring with 5 reads in flight, per-half-step alternating wave priority
# speedup vs baseline: 1.0400x; 1.0169x over previous
.Lan_entry:
	v_cvt_f32_i32_e32 v255, v231
	v_add_f32_e32 v255, 0x42800000, v255
	v_cmp_eq_u32_e32 vcc, 0, v203
	s_nop 1
	v_cndmask_b32_e32 v208, v229, v255, vcc
	v_add_f32_e32 v255, 0x80000000, v208
	v_fma_f32 v96, -v201, |v255|, v253
	v_add_f32_e32 v255, 0xbf800000, v208
	v_fma_f32 v97, -v201, |v255|, v253
	v_add_f32_e32 v255, 0xc0000000, v208
	v_fma_f32 v98, -v201, |v255|, v253
	v_add_f32_e32 v255, 0xc0400000, v208
	v_fma_f32 v99, -v201, |v255|, v253
	v_add_f32_e32 v255, 0xc0800000, v208
	v_fma_f32 v100, -v201, |v255|, v253
	v_add_f32_e32 v255, 0xc0a00000, v208
	v_fma_f32 v101, -v201, |v255|, v253
	v_add_f32_e32 v255, 0xc0c00000, v208
	v_fma_f32 v102, -v201, |v255|, v253
	v_add_f32_e32 v255, 0xc0e00000, v208
	v_fma_f32 v103, -v201, |v255|, v253
	v_add_f32_e32 v255, 0xc1800000, v208
	v_fma_f32 v104, -v201, |v255|, v253
	v_add_f32_e32 v255, 0xc1880000, v208
	v_fma_f32 v105, -v201, |v255|, v253
	v_add_f32_e32 v255, 0xc1900000, v208
	v_fma_f32 v106, -v201, |v255|, v253
	v_add_f32_e32 v255, 0xc1980000, v208
	v_fma_f32 v107, -v201, |v255|, v253
	v_add_f32_e32 v255, 0xc1a00000, v208
	v_fma_f32 v108, -v201, |v255|, v253
	v_add_f32_e32 v255, 0xc1a80000, v208
	v_fma_f32 v109, -v201, |v255|, v253
	v_add_f32_e32 v255, 0xc1b00000, v208
	v_fma_f32 v110, -v201, |v255|, v253
	v_add_f32_e32 v255, 0xc1b80000, v208
	v_fma_f32 v111, -v201, |v255|, v253
	v_mov_b32_e32 v80, 0xff61b1e6
	v_mov_b32_e32 v81, 0xff61b1e6
	v_mov_b32_e32 v82, 0xff61b1e6
	v_mov_b32_e32 v83, 0xff61b1e6
	v_mov_b32_e32 v84, 0xff61b1e6
	v_mov_b32_e32 v85, 0xff61b1e6
	v_mov_b32_e32 v86, 0xff61b1e6
	v_mov_b32_e32 v87, 0xff61b1e6
	v_mov_b32_e32 v88, 0xff61b1e6
	v_mov_b32_e32 v89, 0xff61b1e6
	v_mov_b32_e32 v90, 0xff61b1e6
	v_mov_b32_e32 v91, 0xff61b1e6
	v_mov_b32_e32 v92, 0xff61b1e6
	v_mov_b32_e32 v93, 0xff61b1e6
	v_mov_b32_e32 v94, 0xff61b1e6
	v_mov_b32_e32 v95, 0xff61b1e6
.Lan_327:
	s_cmp_ge_u32 s90, 2
	s_cselect_b32 s94, 1, 0
	s_cmp_lt_i32 s90, s38
	s_cselect_b32 s96, 1, 0
	s_and_b32 s94, s94, s96
	s_cmp_ge_u32 s90, 1
	s_cselect_b32 s95, 1, 0
	s_add_i32 s96, s90, 1
	s_cmp_lt_i32 s96, s38
	s_cselect_b32 s96, 1, 0
	s_and_b32 s95, s95, s96
	s_and_b32 s88, s90, 1
	s_mul_i32 s33, s88, 0x4400
	v_add_u32_e32 v235, s33, v230
	s_add_i32 s87, s90, 1
	s_and_b32 s89, s87, 1
	s_mul_i32 s33, s89, 0x4800
	v_add_u32_e32 v234, s33, v215
	ds_read_b128 v[64:67], v235
	ds_read_b128 v[68:71], v235 offset:32
	ds_read_b128 v[72:75], v235 offset:64
	ds_read_b128 v[76:79], v235 offset:96
	ds_read_b128 v[160:163], v234 offset:34816
	s_cmp_lt_i32 s87, s38
	s_cselect_b64 s[54:55], -1, 0
	s_cmp_ge_i32 s87, s38
	s_cbranch_scc1 .Lan_329
	v_lshl_add_u64 v[244:245], s[62:63], 0, v[206:207]
	v_add_co_u32_e32 v246, vcc, 0x8f61000, v244
	s_nop 1
	v_addc_co_u32_e32 v247, vcc, 0, v245, vcc
	v_add_co_u32_e32 v244, vcc, 0x8f89000, v244
	s_nop 1
	v_addc_co_u32_e32 v245, vcc, 0, v245, vcc
	global_load_dwordx4 v[128:131], v[246:247], off
	global_load_dwordx4 v[132:135], v[244:245], off
.Lan_329:
	s_cmp_lt_i32 s90, s38
	s_cselect_b64 s[56:57], -1, 0
	s_cmp_ge_i32 s90, s38
	s_cbranch_scc1 .Lan_331
	v_lshl_add_u64 v[244:245], s[62:63], 0, v[204:205]
	v_add_co_u32_e32 v246, vcc, 0x18803000, v244
	s_nop 1
	v_addc_co_u32_e32 v247, vcc, 0, v245, vcc
	v_add_co_u32_e32 v244, vcc, 0x18c05000, v244
	s_nop 1
	v_addc_co_u32_e32 v245, vcc, 0, v245, vcc
	global_load_dwordx4 v[136:139], v[246:247], off offset:3968
	global_load_dwordx4 v[140:143], v[244:245], off offset:3968
.Lan_331:
	v_cvt_f32_i32_e32 v237, v231
	v_xor_b32_e32 v236, 0x80000000, v201
	s_cmp_eq_u32 s85, 1
	s_cbranch_scc1 .Lpr_a_c1
	s_setprio 1
	s_branch .Lpr_a_done
.Lpr_a_c1:
	s_setprio 0
.Lpr_a_done:
	s_waitcnt lgkmcnt(4)
	v_mfma_f32_32x32x16_bf16 v[96:111], v[64:67], v[112:115], v[96:111]
	ds_read_b128 v[244:247], v234 offset:34848
	v_exp_f32_e32 v80, v80
	v_exp_f32_e32 v81, v81
	v_add_f32_e32 v238, 0, v80
	v_add_f32_e32 v238, v238, v81
	s_waitcnt lgkmcnt(4)
	v_mfma_f32_32x32x16_bf16 v[96:111], v[68:71], v[116:119], v[96:111]
	ds_read_b128 v[64:67], v234 offset:39424
	v_exp_f32_e32 v82, v82
	v_exp_f32_e32 v83, v83
	v_add_f32_e32 v238, v238, v82
	v_add_f32_e32 v238, v238, v83
	s_waitcnt lgkmcnt(4)
	v_mfma_f32_32x32x16_bf16 v[96:111], v[72:75], v[120:123], v[96:111]
	ds_read_b128 v[68:71], v234 offset:39456
	v_exp_f32_e32 v84, v84
	v_exp_f32_e32 v85, v85
	v_add_f32_e32 v238, v238, v84
	v_add_f32_e32 v238, v238, v85
	s_waitcnt lgkmcnt(4)
	v_mfma_f32_32x32x16_bf16 v[96:111], v[76:79], v[124:127], v[96:111]
	ds_read_b128 v[72:75], v234 offset:44032
	v_exp_f32_e32 v86, v86
	v_exp_f32_e32 v87, v87
	v_add_f32_e32 v238, v238, v86
	v_add_f32_e32 v238, v238, v87
	s_waitcnt lgkmcnt(4)
	v_mfma_f32_32x32x16_bf16 v[48:63], v[160:163], v[144:147], v[48:63]
	ds_read_b128 v[76:79], v234 offset:44064
	v_cvt_pk_bf16_f32 v152, v80, v81
	v_cvt_pk_bf16_f32 v153, v82, v83
	v_cvt_pk_bf16_f32 v154, v84, v85
	v_cvt_pk_bf16_f32 v155, v86, v87
	v_add_f32_e32 v255, 0x42800000, v237
	v_fma_f32 v254, v236, v255, v253
	s_waitcnt lgkmcnt(4)
	v_mfma_f32_32x32x16_bf16 v[48:63], v[244:247], v[148:151], v[48:63]
	ds_read_b128 v[160:163], v234 offset:48640
	v_exp_f32_e32 v88, v88
	v_exp_f32_e32 v89, v89
	v_add_f32_e32 v238, v238, v88
	v_add_f32_e32 v238, v238, v89
	v_fmamk_f32 v80, v201, 0x42000000, v254
	v_fmamk_f32 v81, v201, 0x42040000, v254
	s_waitcnt lgkmcnt(4)
	v_mfma_f32_32x32x16_bf16 v[32:47], v[64:67], v[144:147], v[32:47]
	ds_read_b128 v[244:247], v234 offset:48672
	v_exp_f32_e32 v90, v90
	v_exp_f32_e32 v91, v91
	v_add_f32_e32 v238, v238, v90
	v_add_f32_e32 v238, v238, v91
	v_fmamk_f32 v82, v201, 0x42080000, v254
	v_fmamk_f32 v83, v201, 0x420c0000, v254
	s_waitcnt lgkmcnt(4)
	v_mfma_f32_32x32x16_bf16 v[32:47], v[68:71], v[148:151], v[32:47]
	ds_read_b128 v[64:67], v235 offset:8704
	v_exp_f32_e32 v92, v92
	v_exp_f32_e32 v93, v93
	v_add_f32_e32 v238, v238, v92
	v_add_f32_e32 v238, v238, v93
	v_fmamk_f32 v84, v201, 0x42100000, v254
	v_fmamk_f32 v85, v201, 0x42140000, v254
	s_waitcnt lgkmcnt(4)
	v_mfma_f32_32x32x16_bf16 v[16:31], v[72:75], v[144:147], v[16:31]
	ds_read_b128 v[68:71], v235 offset:8736
	v_exp_f32_e32 v94, v94
	v_exp_f32_e32 v95, v95
	v_add_f32_e32 v238, v238, v94
	v_add_f32_e32 v238, v238, v95
	v_fmamk_f32 v86, v201, 0x42180000, v254
	v_fmamk_f32 v87, v201, 0x421c0000, v254
	s_waitcnt lgkmcnt(4)
	v_mfma_f32_32x32x16_bf16 v[16:31], v[76:79], v[148:151], v[16:31]
	ds_read_b128 v[72:75], v235 offset:8768
	v_cvt_pk_bf16_f32 v156, v88, v89
	v_cvt_pk_bf16_f32 v157, v90, v91
	v_cvt_pk_bf16_f32 v158, v92, v93
	v_cvt_pk_bf16_f32 v159, v94, v95
	s_waitcnt lgkmcnt(4)
	v_mfma_f32_32x32x16_bf16 v[0:15], v[160:163], v[144:147], v[0:15]
	ds_read_b128 v[76:79], v235 offset:8800
	v_fmamk_f32 v88, v201, 0x42400000, v254
	v_fmamk_f32 v89, v201, 0x42440000, v254
	v_fmamk_f32 v90, v201, 0x42480000, v254
	v_fmamk_f32 v91, v201, 0x424c0000, v254
	v_add_f32_e32 v238, v238, v233
	s_waitcnt lgkmcnt(4)
	v_mfma_f32_32x32x16_bf16 v[0:15], v[244:247], v[148:151], v[0:15]
	ds_read_b128 v[160:163], v234 offset:34880
	v_fmamk_f32 v92, v201, 0x42500000, v254
	v_fmamk_f32 v93, v201, 0x42540000, v254
	v_fmamk_f32 v94, v201, 0x42580000, v254
	v_fmamk_f32 v95, v201, 0x425c0000, v254
	s_cmp_lg_u32 s94, 0
	s_cbranch_scc1 .LfixA_skip
	v_cmp_ge_u32_e32 vcc, s90, v203
	v_add_f32_e32 v255, 0x42800000, v237
	s_and_b64 vcc, vcc, s[56:57]
	v_cndmask_b32_e32 v208, v229, v255, vcc
	v_add_f32_e32 v255, 0xc2000000, v208
	v_fma_f32 v80, -v201, |v255|, v253
	v_add_f32_e32 v255, 0xc2040000, v208
	v_fma_f32 v81, -v201, |v255|, v253
	v_add_f32_e32 v255, 0xc2080000, v208
	v_fma_f32 v82, -v201, |v255|, v253
	v_add_f32_e32 v255, 0xc20c0000, v208
	v_fma_f32 v83, -v201, |v255|, v253
	v_add_f32_e32 v255, 0xc2100000, v208
	v_fma_f32 v84, -v201, |v255|, v253
	v_add_f32_e32 v255, 0xc2140000, v208
	v_fma_f32 v85, -v201, |v255|, v253
	v_add_f32_e32 v255, 0xc2180000, v208
	v_fma_f32 v86, -v201, |v255|, v253
	v_add_f32_e32 v255, 0xc21c0000, v208
	v_fma_f32 v87, -v201, |v255|, v253
	v_add_f32_e32 v255, 0xc2400000, v208
	v_fma_f32 v88, -v201, |v255|, v253
	v_add_f32_e32 v255, 0xc2440000, v208
	v_fma_f32 v89, -v201, |v255|, v253
	v_add_f32_e32 v255, 0xc2480000, v208
	v_fma_f32 v90, -v201, |v255|, v253
	v_add_f32_e32 v255, 0xc24c0000, v208
	v_fma_f32 v91, -v201, |v255|, v253
	v_add_f32_e32 v255, 0xc2500000, v208
	v_fma_f32 v92, -v201, |v255|, v253
	v_add_f32_e32 v255, 0xc2540000, v208
	v_fma_f32 v93, -v201, |v255|, v253
	v_add_f32_e32 v255, 0xc2580000, v208
	v_fma_f32 v94, -v201, |v255|, v253
	v_add_f32_e32 v255, 0xc25c0000, v208
	v_fma_f32 v95, -v201, |v255|, v253
	s_nop 1
.LfixA_skip:
	s_cmp_eq_u32 s85, 1
	s_cbranch_scc1 .Lpr_b_c1
	s_setprio 0
	s_branch .Lpr_b_done
.Lpr_b_c1:
	s_setprio 1
.Lpr_b_done:
	s_waitcnt lgkmcnt(4)
	v_mfma_f32_32x32x16_bf16 v[80:95], v[64:67], v[112:115], v[80:95]
	ds_read_b128 v[244:247], v234 offset:34912
	v_exp_f32_e32 v96, v96
	v_exp_f32_e32 v97, v97
	v_add_f32_e32 v233, 0, v96
	v_add_f32_e32 v233, v233, v97
	s_waitcnt lgkmcnt(4)
	v_mfma_f32_32x32x16_bf16 v[80:95], v[68:71], v[116:119], v[80:95]
	ds_read_b128 v[64:67], v234 offset:39488
	v_exp_f32_e32 v98, v98
	v_exp_f32_e32 v99, v99
	v_add_f32_e32 v233, v233, v98
	v_add_f32_e32 v233, v233, v99
	s_waitcnt lgkmcnt(4)
	v_mfma_f32_32x32x16_bf16 v[80:95], v[72:75], v[120:123], v[80:95]
	ds_read_b128 v[68:71], v234 offset:39520
	v_exp_f32_e32 v100, v100
	v_exp_f32_e32 v101, v101
	v_add_f32_e32 v233, v233, v100
	v_add_f32_e32 v233, v233, v101
	s_waitcnt lgkmcnt(4)
	v_mfma_f32_32x32x16_bf16 v[80:95], v[76:79], v[124:127], v[80:95]
	ds_read_b128 v[72:75], v234 offset:44096
	v_exp_f32_e32 v102, v102
	v_exp_f32_e32 v103, v103
	v_add_f32_e32 v233, v233, v102
	v_add_f32_e32 v233, v233, v103
	s_waitcnt lgkmcnt(4)
	v_mfma_f32_32x32x16_bf16 v[48:63], v[160:163], v[152:155], v[48:63]
	ds_read_b128 v[76:79], v234 offset:44128
	v_cvt_pk_bf16_f32 v144, v96, v97
	v_cvt_pk_bf16_f32 v145, v98, v99
	v_cvt_pk_bf16_f32 v146, v100, v101
	v_cvt_pk_bf16_f32 v147, v102, v103
	v_add_f32_e32 v255, 0x43000000, v237
	v_fma_f32 v254, v236, v255, v253
	s_waitcnt lgkmcnt(4)
	v_mfma_f32_32x32x16_bf16 v[48:63], v[244:247], v[156:159], v[48:63]
	ds_read_b128 v[160:163], v234 offset:48704
	v_exp_f32_e32 v104, v104
	v_exp_f32_e32 v105, v105
	v_add_f32_e32 v233, v233, v104
	v_add_f32_e32 v233, v233, v105
	v_fmamk_f32 v96, v201, 0x00000000, v254
	v_fmamk_f32 v97, v201, 0x3f800000, v254
	s_waitcnt lgkmcnt(4)
	v_mfma_f32_32x32x16_bf16 v[32:47], v[64:67], v[152:155], v[32:47]
	ds_read_b128 v[244:247], v234 offset:48736
	v_exp_f32_e32 v106, v106
	v_exp_f32_e32 v107, v107
	v_add_f32_e32 v233, v233, v106
	v_add_f32_e32 v233, v233, v107
	v_fmamk_f32 v98, v201, 0x40000000, v254
	v_fmamk_f32 v99, v201, 0x40400000, v254
	s_waitcnt lgkmcnt(4)
	v_mfma_f32_32x32x16_bf16 v[32:47], v[68:71], v[156:159], v[32:47]
	v_exp_f32_e32 v108, v108
	v_exp_f32_e32 v109, v109
	v_add_f32_e32 v233, v233, v108
	v_add_f32_e32 v233, v233, v109
	v_fmamk_f32 v100, v201, 0x40800000, v254
	v_fmamk_f32 v101, v201, 0x40a00000, v254
	s_waitcnt lgkmcnt(3)
	v_mfma_f32_32x32x16_bf16 v[16:31], v[72:75], v[152:155], v[16:31]
	v_exp_f32_e32 v110, v110
	v_exp_f32_e32 v111, v111
	v_add_f32_e32 v233, v233, v110
	v_add_f32_e32 v233, v233, v111
	v_fmamk_f32 v102, v201, 0x40c00000, v254
	v_fmamk_f32 v103, v201, 0x40e00000, v254
	s_waitcnt lgkmcnt(2)
	v_mfma_f32_32x32x16_bf16 v[16:31], v[76:79], v[156:159], v[16:31]
	v_cvt_pk_bf16_f32 v148, v104, v105
	v_cvt_pk_bf16_f32 v149, v106, v107
	v_cvt_pk_bf16_f32 v150, v108, v109
	v_cvt_pk_bf16_f32 v151, v110, v111
	s_waitcnt lgkmcnt(1)
	v_mfma_f32_32x32x16_bf16 v[0:15], v[160:163], v[152:155], v[0:15]
	v_fmamk_f32 v104, v201, 0x41800000, v254
	v_fmamk_f32 v105, v201, 0x41880000, v254
	v_fmamk_f32 v106, v201, 0x41900000, v254
	v_fmamk_f32 v107, v201, 0x41980000, v254
	v_add_f32_e32 v233, v233, v238
	s_waitcnt lgkmcnt(0)
	v_mfma_f32_32x32x16_bf16 v[0:15], v[244:247], v[156:159], v[0:15]
	v_fmamk_f32 v108, v201, 0x41a00000, v254
	v_fmamk_f32 v109, v201, 0x41a80000, v254
	v_fmamk_f32 v110, v201, 0x41b00000, v254
	v_fmamk_f32 v111, v201, 0x41b80000, v254
	s_cmp_lg_u32 s95, 0
	s_cbranch_scc1 .LfixB_skip
	v_cvt_f32_i32_e32 v255, v231
	v_cmp_ge_u32_e32 vcc, s87, v203
	v_add_f32_e32 v255, 0x43000000, v255
	s_and_b64 vcc, vcc, s[54:55]
	v_cndmask_b32_e32 v208, v229, v255, vcc
	v_add_f32_e32 v255, 0x80000000, v208
	v_fma_f32 v96, -v201, |v255|, v253
	v_add_f32_e32 v255, 0xbf800000, v208
	v_fma_f32 v97, -v201, |v255|, v253
	v_add_f32_e32 v255, 0xc0000000, v208
	v_fma_f32 v98, -v201, |v255|, v253
	v_add_f32_e32 v255, 0xc0400000, v208
	v_fma_f32 v99, -v201, |v255|, v253
	v_add_f32_e32 v255, 0xc0800000, v208
	v_fma_f32 v100, -v201, |v255|, v253
	v_add_f32_e32 v255, 0xc0a00000, v208
	v_fma_f32 v101, -v201, |v255|, v253
	v_add_f32_e32 v255, 0xc0c00000, v208
	v_fma_f32 v102, -v201, |v255|, v253
	v_add_f32_e32 v255, 0xc0e00000, v208
	v_fma_f32 v103, -v201, |v255|, v253
	v_add_f32_e32 v255, 0xc1800000, v208
	v_fma_f32 v104, -v201, |v255|, v253
	v_add_f32_e32 v255, 0xc1880000, v208
	v_fma_f32 v105, -v201, |v255|, v253
	v_add_f32_e32 v255, 0xc1900000, v208
	v_fma_f32 v106, -v201, |v255|, v253
	v_add_f32_e32 v255, 0xc1980000, v208
	v_fma_f32 v107, -v201, |v255|, v253
	v_add_f32_e32 v255, 0xc1a00000, v208
	v_fma_f32 v108, -v201, |v255|, v253
	v_add_f32_e32 v255, 0xc1a80000, v208
	v_fma_f32 v109, -v201, |v255|, v253
	v_add_f32_e32 v255, 0xc1b00000, v208
	v_fma_f32 v110, -v201, |v255|, v253
	v_add_f32_e32 v255, 0xc1b80000, v208
	v_fma_f32 v111, -v201, |v255|, v253
	s_nop 1
.LfixB_skip:
	s_andn2_b64 vcc, exec, s[54:55]
	s_cbranch_vccnz .Lan_343
	s_mulk_i32 s89, 0x4400
	v_add_u32_e32 v255, s89, v212
	s_waitcnt vmcnt(1)
	ds_write_b128 v255, v[128:131]
	s_waitcnt vmcnt(0)
	ds_write_b128 v255, v[132:135] offset:8704
.Lan_343:
	s_andn2_b64 vcc, exec, s[56:57]
	s_cbranch_vccnz .Lan_345
	s_mulk_i32 s88, 0x4800
	v_add_u32_e32 v255, s88, v222
	s_waitcnt vmcnt(1)
	ds_write_b128 v255, v[136:139] offset:34816
	s_waitcnt vmcnt(0)
	ds_write_b128 v255, v[140:143] offset:44032

.LBB0_347:
	s_setprio 0
	ds_bpermute_b32 v64, v211, v233
	s_cmp_eq_u32 s85, 1
	s_waitcnt lgkmcnt(0)
	v_add_f32_e32 v64, v233, v64
	v_div_scale_f32 v65, s[54:55], v64, v64, 1.0
	v_rcp_f32_e32 v66, v65
	v_div_scale_f32 v67, vcc, 1.0, v64, 1.0
	v_fma_f32 v68, -v65, v66, 1.0
	v_fmac_f32_e32 v66, v68, v66
	v_mul_f32_e32 v68, v67, v66
	v_fma_f32 v69, -v65, v68, v67
	v_fmac_f32_e32 v68, v69, v66
	v_fma_f32 v65, -v65, v68, v67
	v_div_fmas_f32 v65, v65, v66, v68
	v_div_fixup_f32 v76, v65, v64, 1.0
	v_pk_mul_f32 v[70:71], v[48:49], v[76:77] op_sel_hi:[1,0]
	v_pk_mul_f32 v[74:75], v[50:51], v[76:77] op_sel_hi:[1,0]
	v_pk_mul_f32 v[66:67], v[52:53], v[76:77] op_sel_hi:[1,0]
	v_pk_mul_f32 v[72:73], v[54:55], v[76:77] op_sel_hi:[1,0]
	v_pk_mul_f32 v[64:65], v[56:57], v[76:77] op_sel_hi:[1,0]
	v_pk_mul_f32 v[68:69], v[58:59], v[76:77] op_sel_hi:[1,0]
	v_pk_mul_f32 v[58:59], v[60:61], v[76:77] op_sel_hi:[1,0]
	v_pk_mul_f32 v[62:63], v[62:63], v[76:77] op_sel_hi:[1,0]
	v_pk_mul_f32 v[54:55], v[32:33], v[76:77] op_sel_hi:[1,0]
	v_pk_mul_f32 v[60:61], v[34:35], v[76:77] op_sel_hi:[1,0]
	v_pk_mul_f32 v[50:51], v[36:37], v[76:77] op_sel_hi:[1,0]
	v_pk_mul_f32 v[56:57], v[38:39], v[76:77] op_sel_hi:[1,0]
	v_pk_mul_f32 v[48:49], v[40:41], v[76:77] op_sel_hi:[1,0]
	v_pk_mul_f32 v[52:53], v[42:43], v[76:77] op_sel_hi:[1,0]
	v_pk_mul_f32 v[42:43], v[44:45], v[76:77] op_sel_hi:[1,0]
	v_pk_mul_f32 v[46:47], v[46:47], v[76:77] op_sel_hi:[1,0]
	v_pk_mul_f32 v[38:39], v[16:17], v[76:77] op_sel_hi:[1,0]
	v_pk_mul_f32 v[44:45], v[18:19], v[76:77] op_sel_hi:[1,0]
	v_pk_mul_f32 v[34:35], v[20:21], v[76:77] op_sel_hi:[1,0]
	v_pk_mul_f32 v[40:41], v[22:23], v[76:77] op_sel_hi:[1,0]
	v_pk_mul_f32 v[32:33], v[24:25], v[76:77] op_sel_hi:[1,0]
	v_pk_mul_f32 v[36:37], v[26:27], v[76:77] op_sel_hi:[1,0]
	v_pk_mul_f32 v[22:23], v[28:29], v[76:77] op_sel_hi:[1,0]
	v_pk_mul_f32 v[26:27], v[30:31], v[76:77] op_sel_hi:[1,0]
	v_pk_mul_f32 v[18:19], v[0:1], v[76:77] op_sel_hi:[1,0]
	v_pk_mul_f32 v[24:25], v[2:3], v[76:77] op_sel_hi:[1,0]
	v_pk_mul_f32 v[16:17], v[4:5], v[76:77] op_sel_hi:[1,0]
	v_pk_mul_f32 v[20:21], v[6:7], v[76:77] op_sel_hi:[1,0]
	v_pk_mul_f32 v[8:9], v[8:9], v[76:77] op_sel_hi:[1,0]
	v_pk_mul_f32 v[0:1], v[10:11], v[76:77] op_sel_hi:[1,0]
	v_pk_mul_f32 v[2:3], v[12:13], v[76:77] op_sel_hi:[1,0]
	v_pk_mul_f32 v[6:7], v[14:15], v[76:77] op_sel_hi:[1,0]
	s_cbranch_scc0 .LBB0_349
	v_lshl_add_u32 v4, s84, 14, v216
	ds_write2st64_b32 v4, v70, v71 offset1:1
	ds_write2st64_b32 v4, v74, v75 offset0:2 offset1:3
	ds_write2st64_b32 v4, v66, v67 offset0:4 offset1:5
	ds_write2st64_b32 v4, v72, v73 offset0:6 offset1:7
	ds_write2st64_b32 v4, v64, v65 offset0:8 offset1:9
	ds_write2st64_b32 v4, v68, v69 offset0:10 offset1:11
	ds_write2st64_b32 v4, v58, v59 offset0:12 offset1:13
	ds_write2st64_b32 v4, v62, v63 offset0:14 offset1:15
	ds_write2st64_b32 v4, v54, v55 offset0:16 offset1:17
	ds_write2st64_b32 v4, v60, v61 offset0:18 offset1:19
	ds_write2st64_b32 v4, v50, v51 offset0:20 offset1:21
	ds_write2st64_b32 v4, v56, v57 offset0:22 offset1:23
	ds_write2st64_b32 v4, v48, v49 offset0:24 offset1:25
	ds_write2st64_b32 v4, v52, v53 offset0:26 offset1:27
	ds_write2st64_b32 v4, v42, v43 offset0:28 offset1:29
	ds_write2st64_b32 v4, v46, v47 offset0:30 offset1:31
	ds_write2st64_b32 v4, v38, v39 offset0:32 offset1:33
	ds_write2st64_b32 v4, v44, v45 offset0:34 offset1:35
	ds_write2st64_b32 v4, v34, v35 offset0:36 offset1:37
	ds_write2st64_b32 v4, v40, v41 offset0:38 offset1:39
	ds_write2st64_b32 v4, v32, v33 offset0:40 offset1:41
	ds_write2st64_b32 v4, v36, v37 offset0:42 offset1:43
	ds_write2st64_b32 v4, v22, v23 offset0:44 offset1:45
	ds_write2st64_b32 v4, v26, v27 offset0:46 offset1:47
	ds_write2st64_b32 v4, v18, v19 offset0:48 offset1:49
	ds_write2st64_b32 v4, v24, v25 offset0:50 offset1:51
	ds_write2st64_b32 v4, v16, v17 offset0:52 offset1:53
	ds_write2st64_b32 v4, v20, v21 offset0:54 offset1:55
	ds_write2st64_b32 v4, v8, v9 offset0:56 offset1:57
	ds_write2st64_b32 v4, v0, v1 offset0:58 offset1:59
	ds_write2st64_b32 v4, v2, v3 offset0:60 offset1:61
	ds_write2st64_b32 v4, v6, v7 offset0:62 offset1:63
